# attention queues: differential items in groups of (heavy, heavy, light), remaining light items last
# speedup vs baseline: 1.0166x; 1.0031x over previous
.LBB0_840:
	s_andn2_b64 vcc, exec, s[38:39]
	s_cbranch_vccnz .LBB0_842
	s_add_i32 s4, s54, -12
	s_mul_i32 s30, s4, 0xab
	s_lshr_b32 s30, s30, 9
	s_mul_i32 s31, s30, 3
	s_sub_i32 s31, s4, s31
	s_lshl_b32 s50, s30, 1
	s_add_i32 s50, s50, s31
	s_andn2_b32 s50, 0x7f, s50
	s_cmp_lt_u32 s31, 2
	s_cselect_b32 s50, s50, s30
	s_cselect_b32 s31, 1, 0
	s_add_i32 s30, s4, 0xffffff80
	s_cmpk_lt_u32 s4, 0xc0
	s_cselect_b32 s31, s31, 0
	s_cselect_b32 s50, s50, s30
	s_cmp_eq_u32 s31, 1
	v_readlane_b32 s4, v250, 18
	v_readlane_b32 s5, v250, 19
	s_cselect_b32 s6, 2, 1
	s_cselect_b32 s30, 3, 0
	s_and_b64 s[4:5], s[4:5], exec
	s_cselect_b32 s6, s30, s6
	s_mov_b64 s[4:5], 0
	s_mov_b32 s55, s71
